# decode-shift kernel plus FFN in-projection XCD remap of the tile id (id mod 8, id div 8) computed with unsigned shift/and instead of the signed sequence, 7 scalar instructions fewer per unit
# baseline (speedup 1.0000x reference)
;     __host__ __device__ bool next(int i, Unit& u) const {
;         const long L = (long)i * G + c; if (L >= nwg) return false;
;         int wgid = (int)L; { const int q = nwg / NXCD, r = nwg % NXCD, xcd = wgid % NXCD, off = wgid / NXCD; wgid = (xcd < r ? xcd * (q + 1) : r * (q + 1) + (xcd - r) * q) + off; }
;         const int nig = WGM * nN, gid = wgid / nig, fm = gid * WGM, gsz = (nM - fm) < WGM ? (nM - fm) : WGM;
;         u.pm = fm + ((wgid % nig) % gsz); u.pn = (wgid % nig) / gsz; u.sw = 0; return true;
.LBB0_107:
	s_add_i32 s58, s58, 1
	s_mul_i32 s4, s58, s36
	s_mul_hi_u32 s5, s58, s28
	s_add_i32 s5, s5, s4
	s_mul_i32 s4, s58, s28
	s_add_u32 s18, s4, s2
	s_addc_u32 s19, s5, s33
	v_cmp_gt_i64_e32 vcc, s[18:19], v[164:165]
	v_cmp_lt_i64_e64 s[4:5], s[18:19], v[162:163]
	s_cbranch_vccnz .LBB0_109
	s_lshr_b32 s15, s18, 3
	s_and_b32 s14, s18, 7
	s_mulk_i32 s14, 0x160
	s_add_i32 s14, s14, s15
	s_mul_hi_i32 s15, s14, 0x2e8ba2e9
	s_lshr_b32 s16, s15, 31
	s_ashr_i32 s15, s15, 5
	s_add_i32 s15, s15, s16
	s_lshl_b32 s16, s15, 3
	s_mulk_i32 s15, 0xb0
	s_sub_i32 s15, s14, s15
	s_lshr_b32 s14, s15, 3
	s_lshl_b32 s17, s14, 3
	s_sub_i32 s15, s15, s17
	s_add_i32 s16, s16, s15
